# nsa window branch: waves 0-3 run unmasked tiles for two query sets sharing K/V fragments, waves 4-7 skip, softmax state merged after loop; 256 VGPRs
# speedup vs baseline: 1.0021x; 1.0021x over previous
.LBB0_1462:
	s_or_b64 exec, exec, s[10:11]
	s_add_i32 s10, s55, 0xfffffe01
	s_ashr_i32 s10, s10, 6
	s_cmpk_gt_u32 s55, 0x1fe
	s_cselect_b32 s10, s10, 0
	s_sub_i32 s14, s72, s10
	s_add_i32 s14, s14, 1
	s_cmp_lt_i32 s14, 1
	s_cbranch_scc1 .LBB0_1416
	s_lshl_b64 s[12:13], s[66:67], 21
	s_add_u32 s15, s8, s12
	s_addc_u32 s21, s9, s13
	s_add_u32 s18, s26, s12
	s_addc_u32 s19, s27, s13
	s_ashr_i32 s11, s10, 31
	s_lshl_b64 s[16:17], s[10:11], 14
	s_add_u32 s18, s18, s16
	s_addc_u32 s19, s19, s17
	s_add_u32 s20, s15, s16
	s_addc_u32 s21, s21, s17
	v_mov_b32_e32 v87, v1
	v_lshl_add_u64 v[52:53], s[20:21], 0, v[86:87]
	v_lshl_add_u64 v[54:55], s[18:19], 0, v[86:87]
	v_lshlrev_b64 v[56:57], 1, v[88:89]
	v_lshl_add_u64 v[58:59], v[52:53], 0, v[56:57]
	v_lshl_add_u64 v[56:57], v[54:55], 0, v[56:57]
	global_load_dwordx4 v[84:87], v[58:59], off
	global_load_dwordx4 v[88:91], v[56:57], off
	v_lshlrev_b64 v[56:57], 1, v[92:93]
	v_lshl_add_u64 v[52:53], v[52:53], 0, v[56:57]
	v_lshl_add_u64 v[54:55], v[54:55], 0, v[56:57]
	global_load_dwordx4 v[92:95], v[52:53], off
	global_load_dwordx4 v[96:99], v[54:55], off
	s_lshl_b32 s15, s10, 6
	s_sub_i32 s10, s55, 51
	v_add3_u32 v80, s10, v105, v104
	s_add_u32 s10, s12, s16
	s_addc_u32 s13, s13, s17
	v_sub_u32_e32 v146, v141, v2
	v_mov_b32_e32 v2, v1
	v_mov_b32_e32 v3, v1
	v_sub_u32_e32 v80, v80, v141
	s_add_u32 s12, s52, s10
	v_mov_b32_e32 v0, v1
	v_mov_b64_e32 v[54:55], v[2:3]
	v_mov_b64_e32 v[58:59], v[2:3]
	s_waitcnt vmcnt(5)
	v_mov_b64_e32 v[62:63], v[2:3]
	s_waitcnt vmcnt(4)
	v_mov_b64_e32 v[66:67], v[2:3]
	v_mov_b64_e32 v[70:71], v[2:3]
	v_mov_b64_e32 v[74:75], v[2:3]
	v_mov_b64_e32 v[78:79], v[2:3]
	v_subrev_u32_e32 v147, s15, v80
	s_addc_u32 s13, s53, s13
	v_mov_b64_e32 v[82:83], v[2:3]
	v_add_u32_e32 v145, 0xfffffe04, v134
	s_mov_b32 s11, 0
	v_mov_b32_e32 v148, 0xc6ea6000
	v_mov_b32_e32 v144, 0
	v_mov_b64_e32 v[52:53], v[0:1]
	v_mov_b64_e32 v[56:57], v[0:1]
	v_mov_b64_e32 v[60:61], v[0:1]
	v_mov_b64_e32 v[64:65], v[0:1]
	v_mov_b64_e32 v[68:69], v[0:1]
	v_mov_b64_e32 v[72:73], v[0:1]
	v_mov_b64_e32 v[76:77], v[0:1]
	v_lshl_add_u64 v[128:129], s[12:13], 0, v[100:101]
	v_lshl_add_u64 v[130:131], s[12:13], 0, v[102:103]
	v_mov_b64_e32 v[80:81], v[0:1]
	s_waitcnt vmcnt(3)
	ds_write_b128 v107, v[84:87]
	s_waitcnt vmcnt(2)
	ds_write_b128 v107, v[88:91] offset:18432
	s_waitcnt vmcnt(1)
	ds_write_b128 v106, v[92:95]
	s_waitcnt vmcnt(0)
	ds_write_b128 v106, v[96:99] offset:18432
	v_lshrrev_b32_e32 v234, 6, v136
	v_and_b32_e32 v233, 63, v136
	v_readfirstlane_b32 s82, v234
	v_readfirstlane_b32 s80, v134
	s_and_b32 s83, s82, 4
	s_lshl_b32 s83, s83, 2
	s_sub_i32 s80, s80, s83
	s_sub_i32 s81, s80, 0x1ec
	s_and_b32 s83, s82, 3
	s_mul_i32 s83, s83, 0x2400
	s_add_i32 s83, s83, 0x16900
	v_lshl_add_u32 v233, v233, 4, s83
	s_cmp_lt_u32 s82, 4
	s_cbranch_scc1 .Lnw_noxq
	ds_write_b128 v233, v[4:7] offset:0
	ds_write_b128 v233, v[8:11] offset:1024
	ds_write_b128 v233, v[12:15] offset:2048
	ds_write_b128 v233, v[16:19] offset:3072
.Lnw_noxq:
	s_waitcnt lgkmcnt(0)
	s_barrier
	s_cmp_lt_u32 s82, 4
	s_cbranch_scc0 .Lnw_noinit
	ds_read_b128 v[214:217], v233 offset:0
	ds_read_b128 v[218:221], v233 offset:1024
	ds_read_b128 v[222:225], v233 offset:2048
	ds_read_b128 v[226:229], v233 offset:3072
	v_mov_b32_e32 v182, 0
	v_mov_b32_e32 v183, 0
	v_mov_b32_e32 v184, 0
	v_mov_b32_e32 v185, 0
	v_mov_b32_e32 v186, 0
	v_mov_b32_e32 v187, 0
	v_mov_b32_e32 v188, 0
	v_mov_b32_e32 v189, 0
	v_mov_b32_e32 v190, 0
	v_mov_b32_e32 v191, 0
	v_mov_b32_e32 v192, 0
	v_mov_b32_e32 v193, 0
	v_mov_b32_e32 v194, 0
	v_mov_b32_e32 v195, 0
	v_mov_b32_e32 v196, 0
	v_mov_b32_e32 v197, 0
	v_mov_b32_e32 v198, 0
	v_mov_b32_e32 v199, 0
	v_mov_b32_e32 v200, 0
	v_mov_b32_e32 v201, 0
	v_mov_b32_e32 v202, 0
	v_mov_b32_e32 v203, 0
	v_mov_b32_e32 v204, 0
	v_mov_b32_e32 v205, 0
	v_mov_b32_e32 v206, 0
	v_mov_b32_e32 v207, 0
	v_mov_b32_e32 v208, 0
	v_mov_b32_e32 v209, 0
	v_mov_b32_e32 v210, 0
	v_mov_b32_e32 v211, 0
	v_mov_b32_e32 v212, 0
	v_mov_b32_e32 v213, 0
	v_mov_b32_e32 v230, 0xc6ea6000
	v_mov_b32_e32 v231, 0
	s_waitcnt lgkmcnt(0)
.Lnw_noinit:
.LBB0_1464:
	s_add_i32 s16, s11, 1
	s_cmp_lt_i32 s16, s14
	s_cselect_b64 s[12:13], -1, 0
	s_cmp_ge_i32 s16, s14
	s_cbranch_scc1 .LBB0_1466
	v_lshl_add_u64 v[2:3], v[128:129], 0, v[126:127]
	s_waitcnt vmcnt(3)
	v_add_co_u32_e32 v84, vcc, 0x10104000, v2
	s_waitcnt vmcnt(1)
	v_lshl_add_u64 v[92:93], v[130:131], 0, v[126:127]
	v_addc_co_u32_e32 v85, vcc, 0, v3, vcc
	v_add_co_u32_e32 v2, vcc, 0x11104000, v2
	s_nop 1
	v_addc_co_u32_e32 v3, vcc, 0, v3, vcc
	global_load_dwordx4 v[84:87], v[84:85], off
	s_nop 0
	global_load_dwordx4 v[88:91], v[2:3], off
	v_add_co_u32_e32 v2, vcc, 0x10104000, v92
	s_nop 1
	v_addc_co_u32_e32 v3, vcc, 0, v93, vcc
	s_waitcnt vmcnt(2)
	v_add_co_u32_e32 v96, vcc, 0x11104000, v92
	s_nop 1
	v_addc_co_u32_e32 v97, vcc, 0, v93, vcc
	global_load_dwordx4 v[92:95], v[2:3], off
	s_nop 0
	global_load_dwordx4 v[96:99], v[96:97], off
.LBB0_1466:
	s_bitcmp1_b32 s11, 0
	s_cselect_b32 s10, 0x9000, 0
	s_add_i32 s17, s10, 16
	s_add_i32 s10, s15, 63
	s_cmp_le_i32 s10, s80
	s_cbranch_scc0 .Lnw_slow
	s_cmp_ge_i32 s15, s81
	s_cbranch_scc0 .Lnw_slow
	s_cmp_lt_u32 s82, 4
	s_cbranch_scc1 .Lnw_dual
	s_branch .Lnw_tail
.Lnw_slow:
	v_add3_u32 v0, s17, v124, v140
	ds_read_b128 v[100:103], v0
	ds_read_b128 v[104:107], v0 offset:64
	ds_read_b128 v[108:111], v0 offset:4608
	ds_read_b128 v[112:115], v0 offset:4672
	s_add_i32 s10, s15, 63
	v_cmp_le_i32_e32 vcc, s10, v134
	s_waitcnt lgkmcnt(3)
	v_mfma_f32_16x16x32_bf16 v[100:103], v[100:103], v[4:7], 0
	v_cmp_ge_i32_e64 s[10:11], s15, v145
	s_and_b64 s[10:11], vcc, s[10:11]
	s_waitcnt lgkmcnt(2)
	v_mfma_f32_16x16x32_bf16 v[158:161], v[104:107], v[8:11], v[100:103]
	s_waitcnt lgkmcnt(1)
	v_mfma_f32_16x16x32_bf16 v[108:111], v[108:111], v[4:7], 0
	s_nop 1
	ds_read_b128 v[100:103], v0 offset:4736
	s_waitcnt lgkmcnt(1)
	v_mfma_f32_16x16x32_bf16 v[104:107], v[112:115], v[8:11], v[108:111]
	s_nop 2
	ds_read_b128 v[108:111], v0 offset:9216
	ds_read_b128 v[112:115], v0 offset:4800
	s_waitcnt lgkmcnt(2)
	v_mfma_f32_16x16x32_bf16 v[152:155], v[100:103], v[12:15], v[104:107]
	ds_read_b128 v[100:103], v0 offset:9280
	s_waitcnt lgkmcnt(2)
	v_mfma_f32_16x16x32_bf16 v[104:107], v[108:111], v[4:7], 0
	ds_read_b128 v[108:111], v0 offset:9344
	s_waitcnt lgkmcnt(1)
	v_mfma_f32_16x16x32_bf16 v[100:103], v[100:103], v[8:11], v[104:107]
	s_nop 4
	ds_read_b128 v[104:107], v0 offset:13824
	ds_read_b128 v[162:165], v0 offset:9408
	ds_read_b128 v[166:169], v0 offset:13952
	ds_read_b128 v[170:173], v0 offset:14016
	s_waitcnt lgkmcnt(4)
	v_mfma_f32_16x16x32_bf16 v[108:111], v[108:111], v[12:15], v[100:103]
	s_nop 2
	ds_read_b128 v[100:103], v0 offset:13888
	s_waitcnt lgkmcnt(4)
	v_mfma_f32_16x16x32_bf16 v[104:107], v[104:107], v[4:7], 0
	ds_read_b128 v[174:177], v0 offset:128
	ds_read_b128 v[178:181], v0 offset:192
	v_cndmask_b32_e64 v0, 0, 1, s[10:11]
	s_waitcnt lgkmcnt(2)
	v_mfma_f32_16x16x32_bf16 v[100:103], v[100:103], v[8:11], v[104:107]
	v_readfirstlane_b32 s10, v0
	s_bitcmp0_b32 s10, 0
	s_mov_b64 s[10:11], -1
	v_mfma_f32_16x16x32_bf16 v[100:103], v[166:169], v[12:15], v[100:103]
	v_mfma_f32_16x16x32_bf16 v[104:107], v[162:165], v[16:19], v[108:111]
	v_mfma_f32_16x16x32_bf16 v[108:111], v[112:115], v[16:19], v[152:155]
	s_waitcnt lgkmcnt(1)
	v_mfma_f32_16x16x32_bf16 v[112:115], v[174:177], v[12:15], v[158:161]
	s_nop 4
	v_mov_b32_e32 v150, v107
	v_mov_b32_e32 v151, v106
	v_mov_b32_e32 v152, v105
	v_mfma_f32_16x16x32_bf16 v[100:103], v[170:173], v[16:19], v[100:103]
	v_mov_b32_e32 v153, v104
	v_mov_b32_e32 v156, v111
	v_mov_b32_e32 v161, v110
	s_waitcnt lgkmcnt(0)
	v_mfma_f32_16x16x32_bf16 v[112:115], v[178:181], v[16:19], v[112:115]
	v_mov_b32_e32 v157, v109
	s_nop 1
	v_mov_b32_e32 v0, v103
	v_mov_b32_e32 v3, v102
	v_mov_b32_e32 v2, v101
	v_mov_b32_e32 v149, v100
	v_mov_b32_e32 v158, v108
	v_mov_b32_e32 v159, v115
	v_mov_b32_e32 v160, v114
	v_mov_b32_e32 v155, v113
	v_mov_b32_e32 v154, v112
	s_cbranch_scc1 .LBB0_1474
	s_andn2_b64 vcc, exec, s[10:11]
	s_cbranch_vccz .LBB0_1475

.Lnw_dual:
	v_add3_u32 v252, s17, v124, v140
	v_add3_u32 v253, s17, v143, v142
	ds_read_b128 v[100:103], v252 offset:0
	ds_read_b128 v[104:107], v252 offset:4608
	ds_read_b128 v[108:111], v252 offset:9216
	ds_read_b128 v[112:115], v252 offset:13824
	v_xor_b32_e32 v240, 0x80000000, v148
	v_xor_b32_e32 v241, 0x80000000, v148
	v_xor_b32_e32 v242, 0x80000000, v148
	v_xor_b32_e32 v243, 0x80000000, v148
	v_xor_b32_e32 v244, 0x80000000, v230
	v_xor_b32_e32 v245, 0x80000000, v230
	v_xor_b32_e32 v246, 0x80000000, v230
	v_xor_b32_e32 v247, 0x80000000, v230
	s_waitcnt lgkmcnt(0)
	s_nop 1
	v_mfma_f32_16x16x32_bf16 v[150:153], v[100:103], v[4:7], v[240:243]
	v_mfma_f32_16x16x32_bf16 v[154:157], v[104:107], v[4:7], v[240:243]
	v_mfma_f32_16x16x32_bf16 v[158:161], v[108:111], v[4:7], v[240:243]
	v_mfma_f32_16x16x32_bf16 v[162:165], v[112:115], v[4:7], v[240:243]
	v_mfma_f32_16x16x32_bf16 v[166:169], v[100:103], v[214:217], v[244:247]
	v_mfma_f32_16x16x32_bf16 v[170:173], v[104:107], v[214:217], v[244:247]
	v_mfma_f32_16x16x32_bf16 v[174:177], v[108:111], v[214:217], v[244:247]
	v_mfma_f32_16x16x32_bf16 v[178:181], v[112:115], v[214:217], v[244:247]
	ds_read_b128 v[100:103], v252 offset:64
	ds_read_b128 v[104:107], v252 offset:4672
	ds_read_b128 v[108:111], v252 offset:9280
	ds_read_b128 v[112:115], v252 offset:13888
	s_waitcnt lgkmcnt(0)
	v_mfma_f32_16x16x32_bf16 v[150:153], v[100:103], v[8:11], v[150:153]
	v_mfma_f32_16x16x32_bf16 v[154:157], v[104:107], v[8:11], v[154:157]
	v_mfma_f32_16x16x32_bf16 v[158:161], v[108:111], v[8:11], v[158:161]
	v_mfma_f32_16x16x32_bf16 v[162:165], v[112:115], v[8:11], v[162:165]
	v_mfma_f32_16x16x32_bf16 v[166:169], v[100:103], v[218:221], v[166:169]
	v_mfma_f32_16x16x32_bf16 v[170:173], v[104:107], v[218:221], v[170:173]
	v_mfma_f32_16x16x32_bf16 v[174:177], v[108:111], v[218:221], v[174:177]
	v_mfma_f32_16x16x32_bf16 v[178:181], v[112:115], v[218:221], v[178:181]
	ds_read_b128 v[100:103], v252 offset:128
	ds_read_b128 v[104:107], v252 offset:4736
	ds_read_b128 v[108:111], v252 offset:9344
	ds_read_b128 v[112:115], v252 offset:13952
	s_waitcnt lgkmcnt(0)
	v_mfma_f32_16x16x32_bf16 v[150:153], v[100:103], v[12:15], v[150:153]
	v_mfma_f32_16x16x32_bf16 v[154:157], v[104:107], v[12:15], v[154:157]
	v_mfma_f32_16x16x32_bf16 v[158:161], v[108:111], v[12:15], v[158:161]
	v_mfma_f32_16x16x32_bf16 v[162:165], v[112:115], v[12:15], v[162:165]
	v_mfma_f32_16x16x32_bf16 v[166:169], v[100:103], v[222:225], v[166:169]
	v_mfma_f32_16x16x32_bf16 v[170:173], v[104:107], v[222:225], v[170:173]
	v_mfma_f32_16x16x32_bf16 v[174:177], v[108:111], v[222:225], v[174:177]
	v_mfma_f32_16x16x32_bf16 v[178:181], v[112:115], v[222:225], v[178:181]
	ds_read_b128 v[100:103], v252 offset:192
	ds_read_b128 v[104:107], v252 offset:4800
	ds_read_b128 v[108:111], v252 offset:9408
	ds_read_b128 v[112:115], v252 offset:14016
	s_waitcnt lgkmcnt(0)
	v_mfma_f32_16x16x32_bf16 v[150:153], v[100:103], v[16:19], v[150:153]
	v_mfma_f32_16x16x32_bf16 v[154:157], v[104:107], v[16:19], v[154:157]
	v_mfma_f32_16x16x32_bf16 v[158:161], v[108:111], v[16:19], v[158:161]
	v_mfma_f32_16x16x32_bf16 v[162:165], v[112:115], v[16:19], v[162:165]
	v_mfma_f32_16x16x32_bf16 v[166:169], v[100:103], v[226:229], v[166:169]
	v_mfma_f32_16x16x32_bf16 v[170:173], v[104:107], v[226:229], v[170:173]
	v_mfma_f32_16x16x32_bf16 v[174:177], v[108:111], v[226:229], v[174:177]
	v_mfma_f32_16x16x32_bf16 v[178:181], v[112:115], v[226:229], v[178:181]
	ds_read_b64_tr_b16 v[100:101], v253 offset:18432
	ds_read_b64_tr_b16 v[102:103], v253 offset:23040
	ds_read_b64_tr_b16 v[104:105], v253 offset:18464
	ds_read_b64_tr_b16 v[106:107], v253 offset:23072
	ds_read_b64_tr_b16 v[108:109], v253 offset:18496
	ds_read_b64_tr_b16 v[110:111], v253 offset:23104
	ds_read_b64_tr_b16 v[112:113], v253 offset:18528
	ds_read_b64_tr_b16 v[114:115], v253 offset:23136
	v_max3_f32 v248, v150, v151, v152
	v_max3_f32 v249, v153, v154, v155
	v_max3_f32 v248, v248, v156, v157
	v_max3_f32 v249, v249, v158, v159
	v_max3_f32 v248, v248, v160, v161
	v_max3_f32 v249, v249, v162, v163
	v_max3_f32 v248, v248, v164, v165
	v_max_f32_e32 v248, v248, v249
	v_cmp_lt_f32_e32 vcc, 0x41000000, v248
	s_cbranch_vccnz .Lft_rescale_nwA
.Lft_resume_nwA:
	v_exp_f32_e32 v150, v150
	v_exp_f32_e32 v151, v151
	v_add_f32_e32 v144, v144, v150
	v_exp_f32_e32 v152, v152
	v_add_f32_e32 v144, v144, v151
	v_exp_f32_e32 v153, v153
	v_add_f32_e32 v144, v144, v152
	v_exp_f32_e32 v154, v154
	v_add_f32_e32 v144, v144, v153
	v_exp_f32_e32 v155, v155
	v_add_f32_e32 v144, v144, v154
	v_exp_f32_e32 v156, v156
	v_add_f32_e32 v144, v144, v155
	v_exp_f32_e32 v157, v157
	v_add_f32_e32 v144, v144, v156
	s_nop 0
	v_add_f32_e32 v144, v144, v157
	v_cvt_pk_bf16_f32 v150, v150, v151
	v_cvt_pk_bf16_f32 v151, v152, v153
	v_cvt_pk_bf16_f32 v152, v154, v155
	v_cvt_pk_bf16_f32 v153, v156, v157
	v_exp_f32_e32 v158, v158
	v_exp_f32_e32 v159, v159
	v_add_f32_e32 v144, v144, v158
	v_exp_f32_e32 v160, v160
	v_add_f32_e32 v144, v144, v159
	v_exp_f32_e32 v161, v161
	v_add_f32_e32 v144, v144, v160
	v_exp_f32_e32 v162, v162
	v_add_f32_e32 v144, v144, v161
	v_exp_f32_e32 v163, v163
	v_add_f32_e32 v144, v144, v162
	v_exp_f32_e32 v164, v164
	v_add_f32_e32 v144, v144, v163
	v_exp_f32_e32 v165, v165
	v_add_f32_e32 v144, v144, v164
	s_nop 0
	v_add_f32_e32 v144, v144, v165
	v_cvt_pk_bf16_f32 v154, v158, v159
	v_cvt_pk_bf16_f32 v155, v160, v161
	v_cvt_pk_bf16_f32 v156, v162, v163
	v_cvt_pk_bf16_f32 v157, v164, v165
	v_max3_f32 v248, v166, v167, v168
	v_max3_f32 v249, v169, v170, v171
	v_max3_f32 v248, v248, v172, v173
	v_max3_f32 v249, v249, v174, v175
	v_max3_f32 v248, v248, v176, v177
	v_max3_f32 v249, v249, v178, v179
	v_max3_f32 v248, v248, v180, v181
	v_max_f32_e32 v248, v248, v249
	v_cmp_lt_f32_e32 vcc, 0x41000000, v248
	s_cbranch_vccnz .Lft_rescale_nwB
.Lft_resume_nwB:
	v_exp_f32_e32 v166, v166
	v_exp_f32_e32 v167, v167
	v_add_f32_e32 v231, v231, v166
	v_exp_f32_e32 v168, v168
	v_add_f32_e32 v231, v231, v167
	v_exp_f32_e32 v169, v169
	v_add_f32_e32 v231, v231, v168
	v_exp_f32_e32 v170, v170
	v_add_f32_e32 v231, v231, v169
	v_exp_f32_e32 v171, v171
	v_add_f32_e32 v231, v231, v170
	v_exp_f32_e32 v172, v172
	v_add_f32_e32 v231, v231, v171
	v_exp_f32_e32 v173, v173
	v_add_f32_e32 v231, v231, v172
	s_nop 0
	v_add_f32_e32 v231, v231, v173
	v_cvt_pk_bf16_f32 v166, v166, v167
	v_cvt_pk_bf16_f32 v167, v168, v169
	v_cvt_pk_bf16_f32 v168, v170, v171
	v_cvt_pk_bf16_f32 v169, v172, v173
	v_exp_f32_e32 v174, v174
	v_exp_f32_e32 v175, v175
	v_add_f32_e32 v231, v231, v174
	v_exp_f32_e32 v176, v176
	v_add_f32_e32 v231, v231, v175
	v_exp_f32_e32 v177, v177
	v_add_f32_e32 v231, v231, v176
	v_exp_f32_e32 v178, v178
	v_add_f32_e32 v231, v231, v177
	v_exp_f32_e32 v179, v179
	v_add_f32_e32 v231, v231, v178
	v_exp_f32_e32 v180, v180
	v_add_f32_e32 v231, v231, v179
	v_exp_f32_e32 v181, v181
	v_add_f32_e32 v231, v231, v180
	s_nop 0
	v_add_f32_e32 v231, v231, v181
	v_cvt_pk_bf16_f32 v170, v174, v175
	v_cvt_pk_bf16_f32 v171, v176, v177
	v_cvt_pk_bf16_f32 v172, v178, v179
	v_cvt_pk_bf16_f32 v173, v180, v181
	s_waitcnt lgkmcnt(7)
	ds_read_b64_tr_b16 v[158:159], v253 offset:18560
	ds_read_b64_tr_b16 v[160:161], v253 offset:23168
	ds_read_b64_tr_b16 v[162:163], v253 offset:18592
	ds_read_b64_tr_b16 v[164:165], v253 offset:23200
	ds_read_b64_tr_b16 v[174:175], v253 offset:18624
	ds_read_b64_tr_b16 v[176:177], v253 offset:23232
	ds_read_b64_tr_b16 v[178:179], v253 offset:18656
	ds_read_b64_tr_b16 v[180:181], v253 offset:23264
	s_waitcnt lgkmcnt(8)
	v_mfma_f32_16x16x32_bf16 v[80:83], v[100:103], v[150:153], v[80:83]
	v_mfma_f32_16x16x32_bf16 v[182:185], v[100:103], v[166:169], v[182:185]
	v_mfma_f32_16x16x32_bf16 v[76:79], v[104:107], v[150:153], v[76:79]
	v_mfma_f32_16x16x32_bf16 v[186:189], v[104:107], v[166:169], v[186:189]
	v_mfma_f32_16x16x32_bf16 v[72:75], v[108:111], v[150:153], v[72:75]
	v_mfma_f32_16x16x32_bf16 v[190:193], v[108:111], v[166:169], v[190:193]
	v_mfma_f32_16x16x32_bf16 v[68:71], v[112:115], v[150:153], v[68:71]
	v_mfma_f32_16x16x32_bf16 v[194:197], v[112:115], v[166:169], v[194:197]
	s_waitcnt lgkmcnt(7)
	ds_read_b64_tr_b16 v[100:101], v253 offset:27648
	ds_read_b64_tr_b16 v[102:103], v253 offset:32256
	ds_read_b64_tr_b16 v[104:105], v253 offset:27680
	ds_read_b64_tr_b16 v[106:107], v253 offset:32288
	ds_read_b64_tr_b16 v[108:109], v253 offset:27712
	ds_read_b64_tr_b16 v[110:111], v253 offset:32320
	ds_read_b64_tr_b16 v[112:113], v253 offset:27744
	ds_read_b64_tr_b16 v[114:115], v253 offset:32352
	s_waitcnt lgkmcnt(8)
	v_mfma_f32_16x16x32_bf16 v[64:67], v[158:161], v[150:153], v[64:67]
	v_mfma_f32_16x16x32_bf16 v[198:201], v[158:161], v[166:169], v[198:201]
	v_mfma_f32_16x16x32_bf16 v[60:63], v[162:165], v[150:153], v[60:63]
	v_mfma_f32_16x16x32_bf16 v[202:205], v[162:165], v[166:169], v[202:205]
	v_mfma_f32_16x16x32_bf16 v[56:59], v[174:177], v[150:153], v[56:59]
	v_mfma_f32_16x16x32_bf16 v[206:209], v[174:177], v[166:169], v[206:209]
	v_mfma_f32_16x16x32_bf16 v[52:55], v[178:181], v[150:153], v[52:55]
	v_mfma_f32_16x16x32_bf16 v[210:213], v[178:181], v[166:169], v[210:213]
	s_waitcnt lgkmcnt(7)
	ds_read_b64_tr_b16 v[158:159], v253 offset:27776
	ds_read_b64_tr_b16 v[160:161], v253 offset:32384
	ds_read_b64_tr_b16 v[162:163], v253 offset:27808
	ds_read_b64_tr_b16 v[164:165], v253 offset:32416
	ds_read_b64_tr_b16 v[174:175], v253 offset:27840
	ds_read_b64_tr_b16 v[176:177], v253 offset:32448
	ds_read_b64_tr_b16 v[178:179], v253 offset:27872
	ds_read_b64_tr_b16 v[180:181], v253 offset:32480
	s_waitcnt lgkmcnt(8)
	v_mfma_f32_16x16x32_bf16 v[80:83], v[100:103], v[154:157], v[80:83]
	v_mfma_f32_16x16x32_bf16 v[182:185], v[100:103], v[170:173], v[182:185]
	v_mfma_f32_16x16x32_bf16 v[76:79], v[104:107], v[154:157], v[76:79]
	v_mfma_f32_16x16x32_bf16 v[186:189], v[104:107], v[170:173], v[186:189]
	v_mfma_f32_16x16x32_bf16 v[72:75], v[108:111], v[154:157], v[72:75]
	v_mfma_f32_16x16x32_bf16 v[190:193], v[108:111], v[170:173], v[190:193]
	v_mfma_f32_16x16x32_bf16 v[68:71], v[112:115], v[154:157], v[68:71]
	v_mfma_f32_16x16x32_bf16 v[194:197], v[112:115], v[170:173], v[194:197]
	s_waitcnt lgkmcnt(0)
	v_mfma_f32_16x16x32_bf16 v[64:67], v[158:161], v[154:157], v[64:67]
	v_mfma_f32_16x16x32_bf16 v[198:201], v[158:161], v[170:173], v[198:201]
	v_mfma_f32_16x16x32_bf16 v[60:63], v[162:165], v[154:157], v[60:63]
	v_mfma_f32_16x16x32_bf16 v[202:205], v[162:165], v[170:173], v[202:205]
	v_mfma_f32_16x16x32_bf16 v[56:59], v[174:177], v[154:157], v[56:59]
	v_mfma_f32_16x16x32_bf16 v[206:209], v[174:177], v[170:173], v[206:209]
	v_mfma_f32_16x16x32_bf16 v[52:55], v[178:181], v[154:157], v[52:55]
	v_mfma_f32_16x16x32_bf16 v[210:213], v[178:181], v[170:173], v[210:213]
.Lnw_tail:
	s_andn2_b64 vcc, exec, s[12:13]
	s_cbranch_vccnz .Lnw_tail2
	s_bitcmp1_b32 s16, 0
	s_cselect_b32 s10, 0x9000, 0
	v_add_u32_e32 v113, s10, v138
	v_add_u32_e32 v114, v113, v139
	v_add_u32_e32 v113, v113, v135
	s_waitcnt vmcnt(3)
	ds_write_b128 v113, v[84:87]
	s_waitcnt vmcnt(2)
	ds_write_b128 v113, v[88:91] offset:18432
	s_waitcnt vmcnt(1)
	ds_write_b128 v114, v[92:95]
	s_waitcnt vmcnt(0)
	ds_write_b128 v114, v[96:99] offset:18432
.Lnw_tail2:
	s_add_i32 s15, s15, 64
	v_subrev_u32_e32 v147, 64, v147
	v_lshl_add_u64 v[128:129], v[128:129], 0, s[64:65]
	s_cmp_lg_u32 s14, s16
	v_lshl_add_u64 v[130:131], v[130:131], 0, s[64:65]
	s_waitcnt lgkmcnt(0)
	s_barrier
	s_cbranch_scc0 .Lnsa_merge
	s_mov_b32 s11, s16
	s_branch .LBB0_1464
.Lft_rescale_nwA:
	v_mov_b32_e32 v249, v248
	s_nop 1
	v_permlane16_swap_b32_e32 v248, v249
	v_max_f32_e32 v249, v249, v248
	v_mov_b32_e32 v248, v249
	s_nop 1
	v_permlane32_swap_b32_e32 v249, v248
	v_max_f32_e32 v248, v249, v248
	v_max_f32_e32 v248, 0, v248
	v_add_f32_e32 v148, v148, v248
	v_sub_f32_e32 v250, 0, v248
	v_exp_f32_e32 v250, v250
	v_sub_f32_e32 v150, v150, v248
	v_sub_f32_e32 v151, v151, v248
	v_sub_f32_e32 v152, v152, v248
	v_sub_f32_e32 v153, v153, v248
	v_sub_f32_e32 v154, v154, v248
	v_sub_f32_e32 v155, v155, v248
	v_sub_f32_e32 v156, v156, v248
	v_sub_f32_e32 v157, v157, v248
	v_sub_f32_e32 v158, v158, v248
	v_sub_f32_e32 v159, v159, v248
	v_sub_f32_e32 v160, v160, v248
	v_sub_f32_e32 v161, v161, v248
	v_sub_f32_e32 v162, v162, v248
	v_sub_f32_e32 v163, v163, v248
	v_sub_f32_e32 v164, v164, v248
	v_sub_f32_e32 v165, v165, v248
	v_mul_f32_e32 v144, v144, v250
	v_pk_mul_f32 v[80:81], v[80:81], v[250:251] op_sel_hi:[1,0]
	v_pk_mul_f32 v[82:83], v[82:83], v[250:251] op_sel_hi:[1,0]
	v_pk_mul_f32 v[76:77], v[76:77], v[250:251] op_sel_hi:[1,0]
	v_pk_mul_f32 v[78:79], v[78:79], v[250:251] op_sel_hi:[1,0]
	v_pk_mul_f32 v[72:73], v[72:73], v[250:251] op_sel_hi:[1,0]
	v_pk_mul_f32 v[74:75], v[74:75], v[250:251] op_sel_hi:[1,0]
	v_pk_mul_f32 v[68:69], v[68:69], v[250:251] op_sel_hi:[1,0]
	v_pk_mul_f32 v[70:71], v[70:71], v[250:251] op_sel_hi:[1,0]
	v_pk_mul_f32 v[64:65], v[64:65], v[250:251] op_sel_hi:[1,0]
	v_pk_mul_f32 v[66:67], v[66:67], v[250:251] op_sel_hi:[1,0]
	v_pk_mul_f32 v[60:61], v[60:61], v[250:251] op_sel_hi:[1,0]
	v_pk_mul_f32 v[62:63], v[62:63], v[250:251] op_sel_hi:[1,0]
	v_pk_mul_f32 v[56:57], v[56:57], v[250:251] op_sel_hi:[1,0]
	v_pk_mul_f32 v[58:59], v[58:59], v[250:251] op_sel_hi:[1,0]
	v_pk_mul_f32 v[52:53], v[52:53], v[250:251] op_sel_hi:[1,0]
	v_pk_mul_f32 v[54:55], v[54:55], v[250:251] op_sel_hi:[1,0]
	s_branch .Lft_resume_nwA
	s_branch .Lft_resume_nwA
.Lft_rescale_nwB:
	v_mov_b32_e32 v249, v248
	s_nop 1
	v_permlane16_swap_b32_e32 v248, v249
	v_max_f32_e32 v249, v249, v248
	v_mov_b32_e32 v248, v249
	s_nop 1
	v_permlane32_swap_b32_e32 v249, v248
	v_max_f32_e32 v248, v249, v248
	v_max_f32_e32 v248, 0, v248
	v_add_f32_e32 v230, v230, v248
	v_sub_f32_e32 v250, 0, v248
	v_exp_f32_e32 v250, v250
	v_sub_f32_e32 v166, v166, v248
	v_sub_f32_e32 v167, v167, v248
	v_sub_f32_e32 v168, v168, v248
	v_sub_f32_e32 v169, v169, v248
	v_sub_f32_e32 v170, v170, v248
	v_sub_f32_e32 v171, v171, v248
	v_sub_f32_e32 v172, v172, v248
	v_sub_f32_e32 v173, v173, v248
	v_sub_f32_e32 v174, v174, v248
	v_sub_f32_e32 v175, v175, v248
	v_sub_f32_e32 v176, v176, v248
	v_sub_f32_e32 v177, v177, v248
	v_sub_f32_e32 v178, v178, v248
	v_sub_f32_e32 v179, v179, v248
	v_sub_f32_e32 v180, v180, v248
	v_sub_f32_e32 v181, v181, v248
	v_mul_f32_e32 v231, v231, v250
	v_pk_mul_f32 v[182:183], v[182:183], v[250:251] op_sel_hi:[1,0]
	v_pk_mul_f32 v[184:185], v[184:185], v[250:251] op_sel_hi:[1,0]
	v_pk_mul_f32 v[186:187], v[186:187], v[250:251] op_sel_hi:[1,0]
	v_pk_mul_f32 v[188:189], v[188:189], v[250:251] op_sel_hi:[1,0]
	v_pk_mul_f32 v[190:191], v[190:191], v[250:251] op_sel_hi:[1,0]
	v_pk_mul_f32 v[192:193], v[192:193], v[250:251] op_sel_hi:[1,0]
	v_pk_mul_f32 v[194:195], v[194:195], v[250:251] op_sel_hi:[1,0]
	v_pk_mul_f32 v[196:197], v[196:197], v[250:251] op_sel_hi:[1,0]
	v_pk_mul_f32 v[198:199], v[198:199], v[250:251] op_sel_hi:[1,0]
	v_pk_mul_f32 v[200:201], v[200:201], v[250:251] op_sel_hi:[1,0]
	v_pk_mul_f32 v[202:203], v[202:203], v[250:251] op_sel_hi:[1,0]
	v_pk_mul_f32 v[204:205], v[204:205], v[250:251] op_sel_hi:[1,0]
	v_pk_mul_f32 v[206:207], v[206:207], v[250:251] op_sel_hi:[1,0]
	v_pk_mul_f32 v[208:209], v[208:209], v[250:251] op_sel_hi:[1,0]
	v_pk_mul_f32 v[210:211], v[210:211], v[250:251] op_sel_hi:[1,0]
	v_pk_mul_f32 v[212:213], v[212:213], v[250:251] op_sel_hi:[1,0]
	s_branch .Lft_resume_nwB
	s_branch .Lft_resume_nwB
.Lnsa_merge:
	s_cmp_lt_u32 s82, 4
	s_cbranch_scc0 .Lnm_sync
	ds_write_b128 v233, v[182:185] offset:0
	ds_write_b128 v233, v[186:189] offset:1024
	ds_write_b128 v233, v[190:193] offset:2048
	ds_write_b128 v233, v[194:197] offset:3072
	ds_write_b128 v233, v[198:201] offset:4096
	ds_write_b128 v233, v[202:205] offset:5120
	ds_write_b128 v233, v[206:209] offset:6144
	ds_write_b128 v233, v[210:213] offset:7168
	ds_write_b64 v233, v[230:231] offset:8192
.Lnm_sync:
	s_waitcnt lgkmcnt(0)
	s_barrier
	s_cmp_lt_u32 s82, 4
	s_cbranch_scc1 .LBB0_1417
	ds_read_b128 v[150:153], v233 offset:0
	ds_read_b128 v[154:157], v233 offset:1024
	ds_read_b128 v[158:161], v233 offset:2048
	ds_read_b128 v[162:165], v233 offset:3072
	ds_read_b128 v[166:169], v233 offset:4096
	ds_read_b128 v[170:173], v233 offset:5120
	ds_read_b128 v[174:177], v233 offset:6144
	ds_read_b128 v[178:181], v233 offset:7168
	ds_read_b64 v[100:101], v233 offset:8192
	s_waitcnt lgkmcnt(0)
	v_max_f32_e32 v106, v148, v100
	v_sub_f32_e32 v102, v148, v106
	v_sub_f32_e32 v104, v100, v106
	v_exp_f32_e32 v102, v102
	v_exp_f32_e32 v104, v104
	s_nop 0
	v_mul_f32_e32 v144, v144, v102
	v_fmac_f32_e32 v144, v101, v104
	v_pk_mul_f32 v[80:81], v[80:81], v[102:103] op_sel_hi:[1,0]
	v_pk_mul_f32 v[82:83], v[82:83], v[102:103] op_sel_hi:[1,0]
	v_pk_mul_f32 v[76:77], v[76:77], v[102:103] op_sel_hi:[1,0]
	v_pk_mul_f32 v[78:79], v[78:79], v[102:103] op_sel_hi:[1,0]
	v_pk_mul_f32 v[72:73], v[72:73], v[102:103] op_sel_hi:[1,0]
	v_pk_mul_f32 v[74:75], v[74:75], v[102:103] op_sel_hi:[1,0]
	v_pk_mul_f32 v[68:69], v[68:69], v[102:103] op_sel_hi:[1,0]
	v_pk_mul_f32 v[70:71], v[70:71], v[102:103] op_sel_hi:[1,0]
	v_pk_mul_f32 v[64:65], v[64:65], v[102:103] op_sel_hi:[1,0]
	v_pk_mul_f32 v[66:67], v[66:67], v[102:103] op_sel_hi:[1,0]
	v_pk_mul_f32 v[60:61], v[60:61], v[102:103] op_sel_hi:[1,0]
	v_pk_mul_f32 v[62:63], v[62:63], v[102:103] op_sel_hi:[1,0]
	v_pk_mul_f32 v[56:57], v[56:57], v[102:103] op_sel_hi:[1,0]
	v_pk_mul_f32 v[58:59], v[58:59], v[102:103] op_sel_hi:[1,0]
	v_pk_mul_f32 v[52:53], v[52:53], v[102:103] op_sel_hi:[1,0]
	v_pk_mul_f32 v[54:55], v[54:55], v[102:103] op_sel_hi:[1,0]
	v_pk_fma_f32 v[80:81], v[150:151], v[104:105], v[80:81] op_sel_hi:[1,0,1]
	v_pk_fma_f32 v[82:83], v[152:153], v[104:105], v[82:83] op_sel_hi:[1,0,1]
	v_pk_fma_f32 v[76:77], v[154:155], v[104:105], v[76:77] op_sel_hi:[1,0,1]
	v_pk_fma_f32 v[78:79], v[156:157], v[104:105], v[78:79] op_sel_hi:[1,0,1]
	v_pk_fma_f32 v[72:73], v[158:159], v[104:105], v[72:73] op_sel_hi:[1,0,1]
	v_pk_fma_f32 v[74:75], v[160:161], v[104:105], v[74:75] op_sel_hi:[1,0,1]
	v_pk_fma_f32 v[68:69], v[162:163], v[104:105], v[68:69] op_sel_hi:[1,0,1]
	v_pk_fma_f32 v[70:71], v[164:165], v[104:105], v[70:71] op_sel_hi:[1,0,1]
	v_pk_fma_f32 v[64:65], v[166:167], v[104:105], v[64:65] op_sel_hi:[1,0,1]
	v_pk_fma_f32 v[66:67], v[168:169], v[104:105], v[66:67] op_sel_hi:[1,0,1]
	v_pk_fma_f32 v[60:61], v[170:171], v[104:105], v[60:61] op_sel_hi:[1,0,1]
	v_pk_fma_f32 v[62:63], v[172:173], v[104:105], v[62:63] op_sel_hi:[1,0,1]
	v_pk_fma_f32 v[56:57], v[174:175], v[104:105], v[56:57] op_sel_hi:[1,0,1]
	v_pk_fma_f32 v[58:59], v[176:177], v[104:105], v[58:59] op_sel_hi:[1,0,1]
	v_pk_fma_f32 v[52:53], v[178:179], v[104:105], v[52:53] op_sel_hi:[1,0,1]
	v_pk_fma_f32 v[54:55], v[180:181], v[104:105], v[54:55] op_sel_hi:[1,0,1]
	s_branch .LBB0_1417

	.amdhsa_kernel _Z8yoco_fwd4Args
		.amdhsa_group_segment_fixed_size 16
		.amdhsa_private_segment_fixed_size 0
		.amdhsa_kernarg_size 512
		.amdhsa_user_sgpr_count 2
		.amdhsa_user_sgpr_dispatch_ptr 0
		.amdhsa_user_sgpr_queue_ptr 0
		.amdhsa_user_sgpr_kernarg_segment_ptr 1
		.amdhsa_user_sgpr_dispatch_id 0
		.amdhsa_user_sgpr_kernarg_preload_length 0
		.amdhsa_user_sgpr_kernarg_preload_offset 0
		.amdhsa_user_sgpr_private_segment_size 0
		.amdhsa_uses_dynamic_stack 0
		.amdhsa_enable_private_segment 0
		.amdhsa_system_sgpr_workgroup_id_x 1
		.amdhsa_system_sgpr_workgroup_id_y 0
		.amdhsa_system_sgpr_workgroup_id_z 0
		.amdhsa_system_sgpr_workgroup_info 0
		.amdhsa_system_vgpr_workitem_id 2
		.amdhsa_next_free_vgpr 256
		.amdhsa_next_free_sgpr 100
		.amdhsa_accum_offset 256
		.amdhsa_reserve_vcc 1
		.amdhsa_float_round_mode_32 0
		.amdhsa_float_round_mode_16_64 0
		.amdhsa_float_denorm_mode_32 3
		.amdhsa_float_denorm_mode_16_64 3
		.amdhsa_dx10_clamp 1
		.amdhsa_ieee_mode 1
		.amdhsa_fp16_overflow 0
		.amdhsa_tg_split 0
		.amdhsa_exception_fp_ieee_invalid_op 0
		.amdhsa_exception_fp_denorm_src 0
		.amdhsa_exception_fp_ieee_div_zero 0
		.amdhsa_exception_fp_ieee_overflow 0
		.amdhsa_exception_fp_ieee_underflow 0
		.amdhsa_exception_fp_ieee_inexact 0
		.amdhsa_exception_int_div_zero 0
	.end_amdhsa_kernel

amdhsa.kernels:
  - .agpr_count:     0
    .args:
      - .offset:         0
        .size:           256
        .value_kind:     by_value
      - .offset:         256
        .size:           4
        .value_kind:     hidden_block_count_x
      - .offset:         260
        .size:           4
        .value_kind:     hidden_block_count_y
      - .offset:         264
        .size:           4
        .value_kind:     hidden_block_count_z
      - .offset:         268
        .size:           2
        .value_kind:     hidden_group_size_x
      - .offset:         270
        .size:           2
        .value_kind:     hidden_group_size_y
      - .offset:         272
        .size:           2
        .value_kind:     hidden_group_size_z
      - .offset:         274
        .size:           2
        .value_kind:     hidden_remainder_x
      - .offset:         276
        .size:           2
        .value_kind:     hidden_remainder_y
      - .offset:         278
        .size:           2
        .value_kind:     hidden_remainder_z
      - .offset:         296
        .size:           8
        .value_kind:     hidden_global_offset_x
      - .offset:         304
        .size:           8
        .value_kind:     hidden_global_offset_y
      - .offset:         312
        .size:           8
        .value_kind:     hidden_global_offset_z
      - .offset:         320
        .size:           2
        .value_kind:     hidden_grid_dims
      - .offset:         344
        .size:           8
        .value_kind:     hidden_multigrid_sync_arg
      - .offset:         376
        .size:           4
        .value_kind:     hidden_dynamic_lds_size
    .group_segment_fixed_size: 16
    .kernarg_segment_align: 8
    .kernarg_segment_size: 512
    .language:       OpenCL C
    .language_version:
      - 2
      - 0
    .max_flat_workgroup_size: 512
    .name:           _Z8yoco_fwd4Args
    .private_segment_fixed_size: 0
    .sgpr_count:     106
    .sgpr_spill_count: 21
    .symbol:         _Z8yoco_fwd4Args.kd
    .uniform_work_group_size: 1
    .uses_dynamic_stack: false
    .vgpr_count:     256
    .vgpr_spill_count: 0
    .wavefront_size: 64
